# Wo GEMM epilogue: loop-invariant gain vectors kept in registers and per-row xs reused, so each row group issues 3 loads and waits once instead of 8 loads in two serialized round trips
# speedup vs baseline: 1.0083x; 1.0083x over previous
; DI unsigned pk2(float lo, float hi) { const f32x2 v = {lo, hi}; const hwbf16x2 b = __builtin_convertvector(v, hwbf16x2); return __builtin_bit_cast(unsigned, b); }
; DI float fsilu(float v) { return v * frcp(1.f + __expf(-v)); }
;     DI void operator()(const f32x4 (&acc)[2][2][4][2], const Unit& u, int wr, int wc, int fr, int fq) const {
;     ...
;                     } else if (mode == EPI_RESID_NORM) {
;                         const size_t ix = (size_t)row * DM + col;
;                         f32x4 r0, r1;
;                         if (resid) { r0 = *(const f32x4*)(resid + ix); r1 = *(const f32x4*)(resid + ix + 4); }
;                         else {
;                             const u32x4 hb = *(const u32x4*)(O + ix); const float xr = rscale[row];
;                             const f32x4 i0 = *(const f32x4*)(bias + col), i1 = *(const f32x4*)(bias + col + 4);
;                             r0[0] = bflo(hb.x) * xr * i0[0]; r0[1] = bfhi(hb.x) * xr * i0[1]; r0[2] = bflo(hb.y) * xr * i0[2]; r0[3] = bfhi(hb.y) * xr * i0[3];
;                             r1[0] = bflo(hb.z) * xr * i1[0]; r1[1] = bfhi(hb.z) * xr * i1[1]; r1[2] = bflo(hb.w) * xr * i1[2]; r1[3] = bfhi(hb.w) * xr * i1[3];
;                         }
;                         v0 = v0 + r0; v1 = v1 + r1;
;                         if (outf) { *(f32x4*)(outf + ix) = v0; *(f32x4*)(outf + ix + 4) = v1; }
;                         u32x4 w; w.x = pk2(v0[0], v0[1]); w.y = pk2(v0[2], v0[3]); w.z = pk2(v1[0], v1[1]); w.w = pk2(v1[2], v1[3]);
;                         *(u32x4*)(O + ix) = w;
;                         rowacc += (v0[0] * v0[0] + v0[1] * v0[1]) + (v0[2] * v0[2] + v0[3] * v0[3]) + (v1[0] * v1[0] + v1[1] * v1[1]) + (v1[2] * v1[2] + v1[3] * v1[3]);
;                     } else {
;                         v0 = v0 * rs; v1 = v1 * rs;
;                         u32x2 w; w.x = pk2(fsilu(v0[0]) * v1[0], fsilu(v0[1]) * v1[1]); w.y = pk2(fsilu(v0[2]) * v1[2], fsilu(v0[3]) * v1[3]);
;                         *(u32x2*)(O + (size_t)row * ldc + (col >> 1)) = w;
;                     }
;                 }
;                 if (mode == EPI_RESID_NORM) {
;                     rowacc += __shfl_xor(rowacc, 16); rowacc += __shfl_xor(rowacc, 32);
;                     if (fq == 0) atomicAdd(rowsq + row, rowacc);
;                 }
.LBB0_939:
	v_lshl_add_u32 v148, s26, 8, v152
	v_ashrrev_i32_e32 v149, 31, v148
	v_lshl_or_b32 v146, s28, 8, v154
	v_lshlrev_b64 v[144:145], 12, v[148:149]
	v_ashrrev_i32_e32 v147, 31, v146
	v_lshl_add_u64 v[144:145], s[62:63], 0, v[144:145]
	v_lshl_add_u64 v[164:165], v[146:147], 1, v[144:145]
	global_load_dwordx4 v[160:163], v[164:165], off
	v_lshl_add_u64 v[144:145], v[148:149], 2, s[10:11]
	global_load_dword v166, v[144:145], off
	v_lshl_add_u64 v[150:151], v[146:147], 2, s[76:77]
	global_load_dwordx4 v[170:173], v[150:151], off
	global_load_dwordx4 v[174:177], v[150:151], off offset:16
	global_load_dwordx4 v[178:181], v[164:165], off offset:256
	s_waitcnt vmcnt(0)
	v_mov_b32_e32 v236, v170
	v_mov_b32_e32 v237, v171
	v_mov_b32_e32 v238, v172
	v_mov_b32_e32 v239, v173
	v_mov_b32_e32 v240, v174
	v_mov_b32_e32 v241, v175
	v_mov_b32_e32 v242, v176
	v_mov_b32_e32 v243, v177
	v_lshlrev_b32_e32 v182, 16, v160
	v_and_b32_e32 v183, 0xffff0000, v160
	v_lshlrev_b32_e32 v160, 16, v161
	v_and_b32_e32 v161, 0xffff0000, v161
	v_lshlrev_b32_e32 v184, 16, v162
	v_and_b32_e32 v185, 0xffff0000, v162
	v_lshlrev_b32_e32 v162, 16, v163
	v_and_b32_e32 v163, 0xffff0000, v163
	v_pk_mul_f32 v[182:183], v[166:167], v[182:183] op_sel_hi:[0,1]
	v_pk_mul_f32 v[160:161], v[166:167], v[160:161] op_sel_hi:[0,1]
	v_pk_mul_f32 v[184:185], v[166:167], v[184:185] op_sel_hi:[0,1]
	v_pk_mul_f32 v[162:163], v[166:167], v[162:163] op_sel_hi:[0,1]
	v_pk_fma_f32 v[172:173], v[172:173], v[160:161], v[126:127]
	v_pk_fma_f32 v[170:171], v[170:171], v[182:183], v[124:125]
	v_pk_fma_f32 v[176:177], v[162:163], v[176:177], v[122:123]
	v_pk_fma_f32 v[174:175], v[184:185], v[174:175], v[120:121]
	v_cvt_pk_bf16_f32 v120, v170, v171
	v_cvt_pk_bf16_f32 v121, v172, v173
	v_cvt_pk_bf16_f32 v122, v174, v175
	v_cvt_pk_bf16_f32 v123, v176, v177
	global_store_dwordx4 v[164:165], v[120:123], off
	global_load_dword v166, v[144:145], off
	v_mul_f32_e32 v159, v171, v171
	v_or_b32_e32 v120, 0x80, v146
	v_ashrrev_i32_e32 v121, 31, v120
	v_lshl_add_u64 v[120:121], v[120:121], 2, s[76:77]
	global_load_dwordx4 v[124:127], v[120:121], off
	global_load_dwordx4 v[160:163], v[120:121], off offset:16
	v_mul_f32_e32 v168, v173, v173
	v_mul_f32_e32 v182, v175, v175
	v_fmac_f32_e32 v159, v170, v170
	v_fmac_f32_e32 v168, v172, v172
	v_lshlrev_b32_e32 v170, 16, v178
	v_and_b32_e32 v171, 0xffff0000, v178
	v_lshlrev_b32_e32 v172, 16, v179
	v_and_b32_e32 v173, 0xffff0000, v179
	v_mul_f32_e32 v183, v177, v177
	v_fmac_f32_e32 v182, v174, v174
	v_lshlrev_b32_e32 v174, 16, v180
	v_and_b32_e32 v175, 0xffff0000, v180
	v_fmac_f32_e32 v183, v176, v176
	v_lshlrev_b32_e32 v176, 16, v181
	v_and_b32_e32 v177, 0xffff0000, v181
	v_and_b32_e32 v123, 64, v158
	v_xor_b32_e32 v122, 16, v158
	v_add_u32_e32 v123, 64, v123
	v_add_f32_e32 v159, v159, v168
	v_cmp_lt_i32_e32 vcc, v122, v123
	v_add_f32_e32 v159, v182, v159
	v_add_f32_e32 v159, v183, v159
	v_cndmask_b32_e32 v122, v158, v122, vcc
	v_lshlrev_b32_e32 v122, 2, v122
	s_waitcnt vmcnt(2)
	v_pk_mul_f32 v[170:171], v[166:167], v[170:171] op_sel_hi:[0,1]
	v_pk_mul_f32 v[172:173], v[166:167], v[172:173] op_sel_hi:[0,1]
	v_pk_mul_f32 v[174:175], v[166:167], v[174:175] op_sel_hi:[0,1]
	v_pk_mul_f32 v[176:177], v[166:167], v[176:177] op_sel_hi:[0,1]
	s_waitcnt vmcnt(1)
	v_mov_b32_e32 v244, v124
	v_mov_b32_e32 v245, v125
	v_mov_b32_e32 v246, v126
	v_mov_b32_e32 v247, v127
	v_pk_fma_f32 v[118:119], v[126:127], v[172:173], v[118:119]
	v_pk_fma_f32 v[116:117], v[124:125], v[170:171], v[116:117]
	s_waitcnt vmcnt(0)
	v_mov_b32_e32 v248, v160
	v_mov_b32_e32 v249, v161
	v_mov_b32_e32 v250, v162
	v_mov_b32_e32 v251, v163
	v_pk_fma_f32 v[126:127], v[174:175], v[160:161], v[112:113]
	v_mul_f32_e32 v112, v117, v117
	v_mul_f32_e32 v113, v119, v119
	v_pk_fma_f32 v[124:125], v[176:177], v[162:163], v[114:115]
	v_mul_f32_e32 v114, v127, v127
	v_fmac_f32_e32 v112, v116, v116
	v_fmac_f32_e32 v113, v118, v118
	v_mul_f32_e32 v115, v125, v125
	v_fmac_f32_e32 v114, v126, v126
	v_add_f32_e32 v112, v112, v113
	v_fmac_f32_e32 v115, v124, v124
	v_add_f32_e32 v112, v114, v112
	v_add_f32_e32 v112, v115, v112
	v_add_f32_e32 v112, v159, v112
	ds_bpermute_b32 v113, v122, v112
	v_xor_b32_e32 v114, 32, v158
	v_cmp_lt_i32_e32 vcc, v114, v123
	v_cvt_pk_bf16_f32 v116, v116, v117
	v_cvt_pk_bf16_f32 v117, v118, v119
	v_cndmask_b32_e32 v114, v158, v114, vcc
	s_waitcnt lgkmcnt(0)
	v_add_f32_e32 v112, v112, v113
	v_lshlrev_b32_e32 v114, 2, v114
	ds_bpermute_b32 v113, v114, v112
	v_cvt_pk_bf16_f32 v118, v126, v127
	v_cvt_pk_bf16_f32 v119, v124, v125
	global_store_dwordx4 v[164:165], v[116:119], off offset:256
	s_and_saveexec_b64 s[26:27], s[4:5]
	s_cbranch_execz .LBB0_941
	v_lshl_add_u64 v[116:117], v[148:149], 2, s[74:75]
	s_waitcnt lgkmcnt(0)
	v_add_f32_e32 v112, v112, v113
	global_atomic_add_f32 v[116:117], v112, off
; DI unsigned pk2(float lo, float hi) { const f32x2 v = {lo, hi}; const hwbf16x2 b = __builtin_convertvector(v, hwbf16x2); return __builtin_bit_cast(unsigned, b); }
; DI float fsilu(float v) { return v * frcp(1.f + __expf(-v)); }
;     DI void operator()(const f32x4 (&acc)[2][2][4][2], const Unit& u, int wr, int wc, int fr, int fq) const {
;     ...
;                     } else if (mode == EPI_RESID_NORM) {
;                         const size_t ix = (size_t)row * DM + col;
;                         f32x4 r0, r1;
;                         if (resid) { r0 = *(const f32x4*)(resid + ix); r1 = *(const f32x4*)(resid + ix + 4); }
;                         else {
;                             const u32x4 hb = *(const u32x4*)(O + ix); const float xr = rscale[row];
;                             const f32x4 i0 = *(const f32x4*)(bias + col), i1 = *(const f32x4*)(bias + col + 4);
;                             r0[0] = bflo(hb.x) * xr * i0[0]; r0[1] = bfhi(hb.x) * xr * i0[1]; r0[2] = bflo(hb.y) * xr * i0[2]; r0[3] = bfhi(hb.y) * xr * i0[3];
;                             r1[0] = bflo(hb.z) * xr * i1[0]; r1[1] = bfhi(hb.z) * xr * i1[1]; r1[2] = bflo(hb.w) * xr * i1[2]; r1[3] = bfhi(hb.w) * xr * i1[3];
;                         }
;                         v0 = v0 + r0; v1 = v1 + r1;
;                         if (outf) { *(f32x4*)(outf + ix) = v0; *(f32x4*)(outf + ix + 4) = v1; }
;                         u32x4 w; w.x = pk2(v0[0], v0[1]); w.y = pk2(v0[2], v0[3]); w.z = pk2(v1[0], v1[1]); w.w = pk2(v1[2], v1[3]);
;                         *(u32x4*)(O + ix) = w;
;                         rowacc += (v0[0] * v0[0] + v0[1] * v0[1]) + (v0[2] * v0[2] + v0[3] * v0[3]) + (v1[0] * v1[0] + v1[1] * v1[1]) + (v1[2] * v1[2] + v1[3] * v1[3]);
;                     } else {
;                         v0 = v0 * rs; v1 = v1 * rs;
;                         u32x2 w; w.x = pk2(fsilu(v0[0]) * v1[0], fsilu(v0[1]) * v1[1]); w.y = pk2(fsilu(v0[2]) * v1[2], fsilu(v0[3]) * v1[3]);
;                         *(u32x2*)(O + (size_t)row * ldc + (col >> 1)) = w;
;                     }
;                 }
;                 if (mode == EPI_RESID_NORM) {
;                     rowacc += __shfl_xor(rowacc, 16); rowacc += __shfl_xor(rowacc, 32);
;                     if (fq == 0) atomicAdd(rowsq + row, rowacc);
;                 }
.LBB0_941:
	s_or_b64 exec, exec, s[26:27]
	v_or_b32_e32 v112, 16, v148
	s_waitcnt lgkmcnt(0)
	v_ashrrev_i32_e32 v113, 31, v112
	v_lshlrev_b64 v[116:117], 12, v[112:113]
	v_lshl_add_u64 v[116:117], s[62:63], 0, v[116:117]
	v_lshl_add_u64 v[164:165], v[146:147], 1, v[116:117]
	global_load_dwordx4 v[116:119], v[164:165], off
	v_lshl_add_u64 v[174:175], v[112:113], 2, s[10:11]
	global_load_dword v166, v[174:175], off
	global_load_dwordx4 v[170:173], v[164:165], off offset:256
	s_waitcnt vmcnt(2)
	v_lshlrev_b32_e32 v176, 16, v116
	v_and_b32_e32 v177, 0xffff0000, v116
	v_lshlrev_b32_e32 v116, 16, v117
	v_and_b32_e32 v117, 0xffff0000, v117
	v_lshlrev_b32_e32 v178, 16, v118
	v_and_b32_e32 v179, 0xffff0000, v118
	v_lshlrev_b32_e32 v118, 16, v119
	v_and_b32_e32 v119, 0xffff0000, v119
	s_waitcnt vmcnt(1)
	v_pk_mul_f32 v[176:177], v[166:167], v[176:177] op_sel_hi:[0,1]
	v_pk_mul_f32 v[116:117], v[166:167], v[116:117] op_sel_hi:[0,1]
	v_pk_mul_f32 v[178:179], v[166:167], v[178:179] op_sel_hi:[0,1]
	v_pk_mul_f32 v[118:119], v[166:167], v[118:119] op_sel_hi:[0,1]
	v_pk_fma_f32 v[116:117], v[238:239], v[116:117], v[110:111]
	v_pk_fma_f32 v[124:125], v[236:237], v[176:177], v[108:109]
	v_pk_fma_f32 v[118:119], v[118:119], v[242:243], v[106:107]
	v_pk_fma_f32 v[126:127], v[178:179], v[240:241], v[104:105]
	v_cvt_pk_bf16_f32 v104, v124, v125
	v_cvt_pk_bf16_f32 v105, v116, v117
	v_cvt_pk_bf16_f32 v106, v126, v127
	v_cvt_pk_bf16_f32 v107, v118, v119
	global_store_dwordx4 v[164:165], v[104:107], off
	s_nop 0
	v_mul_f32_e32 v115, v125, v125
	v_mul_f32_e32 v117, v117, v117
	v_mul_f32_e32 v123, v127, v127
	v_fmac_f32_e32 v115, v124, v124
	v_fmac_f32_e32 v117, v116, v116
	v_mul_f32_e32 v119, v119, v119
	v_fmac_f32_e32 v123, v126, v126
	v_add_f32_e32 v115, v115, v117
	s_waitcnt vmcnt(1)
	v_lshlrev_b32_e32 v162, 16, v170
	v_and_b32_e32 v163, 0xffff0000, v170
	v_lshlrev_b32_e32 v170, 16, v171
	v_and_b32_e32 v171, 0xffff0000, v171
	v_fmac_f32_e32 v119, v118, v118
	v_add_f32_e32 v115, v123, v115
	v_lshlrev_b32_e32 v174, 16, v172
	v_and_b32_e32 v175, 0xffff0000, v172
	v_add_f32_e32 v115, v119, v115
	v_lshlrev_b32_e32 v172, 16, v173
	v_and_b32_e32 v173, 0xffff0000, v173
	v_pk_mul_f32 v[116:117], v[166:167], v[162:163] op_sel_hi:[0,1]
	v_pk_mul_f32 v[118:119], v[166:167], v[170:171] op_sel_hi:[0,1]
	v_pk_mul_f32 v[124:125], v[166:167], v[174:175] op_sel_hi:[0,1]
	v_pk_fma_f32 v[102:103], v[246:247], v[118:119], v[102:103]
	v_pk_fma_f32 v[100:101], v[244:245], v[116:117], v[100:101]
	v_pk_mul_f32 v[126:127], v[166:167], v[172:173] op_sel_hi:[0,1]
	v_pk_fma_f32 v[106:107], v[124:125], v[248:249], v[96:97]
	v_mul_f32_e32 v96, v101, v101
	v_mul_f32_e32 v97, v103, v103
	v_pk_fma_f32 v[104:105], v[126:127], v[250:251], v[98:99]
	v_mul_f32_e32 v98, v107, v107
	v_fmac_f32_e32 v96, v100, v100
	v_fmac_f32_e32 v97, v102, v102
	v_mul_f32_e32 v99, v105, v105
	v_fmac_f32_e32 v98, v106, v106
	v_add_f32_e32 v96, v96, v97
	v_add_f32_e32 v96, v98, v96
	v_fmac_f32_e32 v99, v104, v104
	v_add_f32_e32 v96, v99, v96
	v_add_f32_e32 v96, v115, v96
	ds_bpermute_b32 v97, v122, v96
	v_cvt_pk_bf16_f32 v98, v100, v101
	v_cvt_pk_bf16_f32 v99, v102, v103
	v_cvt_pk_bf16_f32 v100, v106, v107
	v_cvt_pk_bf16_f32 v101, v104, v105
	s_waitcnt lgkmcnt(0)
	v_add_f32_e32 v96, v96, v97
	ds_bpermute_b32 v97, v114, v96
	global_store_dwordx4 v[164:165], v[98:101], off offset:256
	s_and_saveexec_b64 s[26:27], s[4:5]
	s_cbranch_execz .LBB0_943
	v_lshl_add_u64 v[98:99], v[112:113], 2, s[74:75]
	s_waitcnt lgkmcnt(0)
	v_add_f32_e32 v96, v96, v97
	global_atomic_add_f32 v[98:99], v96, off
.LBB0_943:
	s_or_b64 exec, exec, s[26:27]
	v_or_b32_e32 v96, 32, v148
	s_waitcnt lgkmcnt(0)
	v_ashrrev_i32_e32 v97, 31, v96
	v_lshlrev_b64 v[98:99], 12, v[96:97]
	v_lshl_add_u64 v[98:99], s[62:63], 0, v[98:99]
	v_lshl_add_u64 v[116:117], v[146:147], 1, v[98:99]
	global_load_dwordx4 v[98:101], v[116:117], off
	v_lshl_add_u64 v[118:119], v[96:97], 2, s[10:11]
	global_load_dword v124, v[118:119], off
	global_load_dwordx4 v[110:113], v[116:117], off offset:256
	s_waitcnt vmcnt(2)
	v_lshlrev_b32_e32 v126, 16, v98
	v_and_b32_e32 v127, 0xffff0000, v98
	v_lshlrev_b32_e32 v98, 16, v99
	v_and_b32_e32 v99, 0xffff0000, v99
	v_lshlrev_b32_e32 v160, 16, v100
	v_and_b32_e32 v161, 0xffff0000, v100
	v_lshlrev_b32_e32 v100, 16, v101
	v_and_b32_e32 v101, 0xffff0000, v101
	s_waitcnt vmcnt(1)
	v_pk_mul_f32 v[126:127], v[124:125], v[126:127] op_sel_hi:[0,1]
	v_pk_mul_f32 v[98:99], v[124:125], v[98:99] op_sel_hi:[0,1]
	v_pk_mul_f32 v[160:161], v[124:125], v[160:161] op_sel_hi:[0,1]
	v_pk_mul_f32 v[100:101], v[124:125], v[100:101] op_sel_hi:[0,1]
	v_pk_fma_f32 v[98:99], v[238:239], v[98:99], v[94:95]
	v_pk_fma_f32 v[102:103], v[236:237], v[126:127], v[92:93]
	v_pk_fma_f32 v[100:101], v[100:101], v[242:243], v[90:91]
	v_pk_fma_f32 v[104:105], v[160:161], v[240:241], v[88:89]
	v_cvt_pk_bf16_f32 v88, v102, v103
	v_cvt_pk_bf16_f32 v89, v98, v99
	v_cvt_pk_bf16_f32 v90, v104, v105
	v_cvt_pk_bf16_f32 v91, v100, v101
	global_store_dwordx4 v[116:117], v[88:91], off
	s_nop 0
	v_mul_f32_e32 v103, v103, v103
	v_mul_f32_e32 v99, v99, v99
	v_mul_f32_e32 v105, v105, v105
	v_fmac_f32_e32 v103, v102, v102
	v_fmac_f32_e32 v99, v98, v98
	v_mul_f32_e32 v101, v101, v101
	v_fmac_f32_e32 v105, v104, v104
	v_add_f32_e32 v98, v103, v99
	v_fmac_f32_e32 v101, v100, v100
	v_add_f32_e32 v98, v105, v98
	s_waitcnt vmcnt(1)
	v_lshlrev_b32_e32 v108, 16, v110
	v_and_b32_e32 v109, 0xffff0000, v110
	v_lshlrev_b32_e32 v110, 16, v111
	v_and_b32_e32 v111, 0xffff0000, v111
	v_add_f32_e32 v107, v101, v98
	v_lshlrev_b32_e32 v118, 16, v112
	v_and_b32_e32 v119, 0xffff0000, v112
	v_lshlrev_b32_e32 v112, 16, v113
	v_and_b32_e32 v113, 0xffff0000, v113
	v_pk_mul_f32 v[98:99], v[124:125], v[108:109] op_sel_hi:[0,1]
	v_pk_mul_f32 v[100:101], v[124:125], v[110:111] op_sel_hi:[0,1]
	v_pk_mul_f32 v[102:103], v[124:125], v[118:119] op_sel_hi:[0,1]
	v_pk_fma_f32 v[86:87], v[246:247], v[100:101], v[86:87]
	v_pk_fma_f32 v[84:85], v[244:245], v[98:99], v[84:85]
	v_pk_mul_f32 v[104:105], v[124:125], v[112:113] op_sel_hi:[0,1]
	v_pk_fma_f32 v[90:91], v[102:103], v[248:249], v[80:81]
	v_mul_f32_e32 v80, v85, v85
	v_mul_f32_e32 v81, v87, v87
	v_pk_fma_f32 v[88:89], v[104:105], v[250:251], v[82:83]
	v_mul_f32_e32 v82, v91, v91
	v_fmac_f32_e32 v80, v84, v84
	v_fmac_f32_e32 v81, v86, v86
	v_mul_f32_e32 v83, v89, v89
	v_fmac_f32_e32 v82, v90, v90
	v_add_f32_e32 v80, v80, v81
	v_add_f32_e32 v80, v82, v80
	v_fmac_f32_e32 v83, v88, v88
	v_add_f32_e32 v80, v83, v80
	v_add_f32_e32 v80, v107, v80
	ds_bpermute_b32 v81, v122, v80
	v_cvt_pk_bf16_f32 v82, v84, v85
	v_cvt_pk_bf16_f32 v83, v86, v87
	v_cvt_pk_bf16_f32 v84, v90, v91
	v_cvt_pk_bf16_f32 v85, v88, v89
	s_waitcnt lgkmcnt(0)
	v_add_f32_e32 v80, v80, v81
	ds_bpermute_b32 v81, v114, v80
	global_store_dwordx4 v[116:117], v[82:85], off offset:256
	s_and_saveexec_b64 s[26:27], s[4:5]
	s_cbranch_execz .LBB0_945
	v_lshl_add_u64 v[82:83], v[96:97], 2, s[74:75]
	s_waitcnt lgkmcnt(0)
	v_add_f32_e32 v80, v80, v81
	global_atomic_add_f32 v[82:83], v80, off
; DI unsigned pk2(float lo, float hi) { const f32x2 v = {lo, hi}; const hwbf16x2 b = __builtin_convertvector(v, hwbf16x2); return __builtin_bit_cast(unsigned, b); }
; DI float fsilu(float v) { return v * frcp(1.f + __expf(-v)); }
;     DI void operator()(const f32x4 (&acc)[2][2][4][2], const Unit& u, int wr, int wc, int fr, int fq) const {
;     ...
;                     } else if (mode == EPI_RESID_NORM) {
;                         const size_t ix = (size_t)row * DM + col;
;                         f32x4 r0, r1;
;                         if (resid) { r0 = *(const f32x4*)(resid + ix); r1 = *(const f32x4*)(resid + ix + 4); }
;                         else {
;                             const u32x4 hb = *(const u32x4*)(O + ix); const float xr = rscale[row];
;                             const f32x4 i0 = *(const f32x4*)(bias + col), i1 = *(const f32x4*)(bias + col + 4);
;                             r0[0] = bflo(hb.x) * xr * i0[0]; r0[1] = bfhi(hb.x) * xr * i0[1]; r0[2] = bflo(hb.y) * xr * i0[2]; r0[3] = bfhi(hb.y) * xr * i0[3];
;                             r1[0] = bflo(hb.z) * xr * i1[0]; r1[1] = bfhi(hb.z) * xr * i1[1]; r1[2] = bflo(hb.w) * xr * i1[2]; r1[3] = bfhi(hb.w) * xr * i1[3];
;                         }
;                         v0 = v0 + r0; v1 = v1 + r1;
;                         if (outf) { *(f32x4*)(outf + ix) = v0; *(f32x4*)(outf + ix + 4) = v1; }
;                         u32x4 w; w.x = pk2(v0[0], v0[1]); w.y = pk2(v0[2], v0[3]); w.z = pk2(v1[0], v1[1]); w.w = pk2(v1[2], v1[3]);
;                         *(u32x4*)(O + ix) = w;
;                         rowacc += (v0[0] * v0[0] + v0[1] * v0[1]) + (v0[2] * v0[2] + v0[3] * v0[3]) + (v1[0] * v1[0] + v1[1] * v1[1]) + (v1[2] * v1[2] + v1[3] * v1[3]);
;                     } else {
;                         v0 = v0 * rs; v1 = v1 * rs;
;                         u32x2 w; w.x = pk2(fsilu(v0[0]) * v1[0], fsilu(v0[1]) * v1[1]); w.y = pk2(fsilu(v0[2]) * v1[2], fsilu(v0[3]) * v1[3]);
;                         *(u32x2*)(O + (size_t)row * ldc + (col >> 1)) = w;
;                     }
;                 }
;                 if (mode == EPI_RESID_NORM) {
;                     rowacc += __shfl_xor(rowacc, 16); rowacc += __shfl_xor(rowacc, 32);
;                     if (fq == 0) atomicAdd(rowsq + row, rowacc);
;                 }
.LBB0_945:
	s_or_b64 exec, exec, s[26:27]
	v_or_b32_e32 v80, 48, v148
	s_waitcnt lgkmcnt(0)
	v_ashrrev_i32_e32 v81, 31, v80
	v_lshlrev_b64 v[82:83], 12, v[80:81]
	v_lshl_add_u64 v[82:83], s[62:63], 0, v[82:83]
	v_lshl_add_u64 v[98:99], v[146:147], 1, v[82:83]
	global_load_dwordx4 v[82:85], v[98:99], off
	v_lshl_add_u64 v[100:101], v[80:81], 2, s[10:11]
	global_load_dword v102, v[100:101], off
	global_load_dwordx4 v[94:97], v[98:99], off offset:256
	s_waitcnt vmcnt(2)
	v_lshlrev_b32_e32 v104, 16, v82
	v_and_b32_e32 v105, 0xffff0000, v82
	v_lshlrev_b32_e32 v82, 16, v83
	v_and_b32_e32 v83, 0xffff0000, v83
	v_lshlrev_b32_e32 v106, 16, v84
	v_and_b32_e32 v107, 0xffff0000, v84
	v_lshlrev_b32_e32 v84, 16, v85
	v_and_b32_e32 v85, 0xffff0000, v85
	s_waitcnt vmcnt(1)
	v_pk_mul_f32 v[104:105], v[102:103], v[104:105] op_sel_hi:[0,1]
	v_pk_mul_f32 v[82:83], v[102:103], v[82:83] op_sel_hi:[0,1]
	v_pk_mul_f32 v[106:107], v[102:103], v[106:107] op_sel_hi:[0,1]
	v_pk_mul_f32 v[84:85], v[102:103], v[84:85] op_sel_hi:[0,1]
	v_pk_fma_f32 v[82:83], v[238:239], v[82:83], v[78:79]
	v_pk_fma_f32 v[86:87], v[236:237], v[104:105], v[76:77]
	v_pk_fma_f32 v[84:85], v[84:85], v[242:243], v[74:75]
	v_pk_fma_f32 v[88:89], v[106:107], v[240:241], v[72:73]
	v_cvt_pk_bf16_f32 v72, v86, v87
	v_cvt_pk_bf16_f32 v73, v82, v83
	v_cvt_pk_bf16_f32 v74, v88, v89
	v_cvt_pk_bf16_f32 v75, v84, v85
	global_store_dwordx4 v[98:99], v[72:75], off
	s_nop 0
	v_mul_f32_e32 v87, v87, v87
	v_mul_f32_e32 v83, v83, v83
	v_mul_f32_e32 v89, v89, v89
	v_fmac_f32_e32 v87, v86, v86
	v_fmac_f32_e32 v83, v82, v82
	v_mul_f32_e32 v85, v85, v85
	v_fmac_f32_e32 v89, v88, v88
	v_add_f32_e32 v82, v87, v83
	v_fmac_f32_e32 v85, v84, v84
	v_add_f32_e32 v82, v89, v82
	s_waitcnt vmcnt(1)
	v_lshlrev_b32_e32 v92, 16, v94
	v_and_b32_e32 v93, 0xffff0000, v94
	v_lshlrev_b32_e32 v94, 16, v95
	v_and_b32_e32 v95, 0xffff0000, v95
	v_add_f32_e32 v91, v85, v82
	v_lshlrev_b32_e32 v100, 16, v96
	v_and_b32_e32 v101, 0xffff0000, v96
	v_lshlrev_b32_e32 v96, 16, v97
	v_and_b32_e32 v97, 0xffff0000, v97
	v_pk_mul_f32 v[82:83], v[102:103], v[92:93] op_sel_hi:[0,1]
	v_pk_mul_f32 v[84:85], v[102:103], v[94:95] op_sel_hi:[0,1]
	v_pk_mul_f32 v[86:87], v[102:103], v[100:101] op_sel_hi:[0,1]
	v_pk_fma_f32 v[70:71], v[246:247], v[84:85], v[70:71]
	v_pk_fma_f32 v[68:69], v[244:245], v[82:83], v[68:69]
	v_pk_mul_f32 v[88:89], v[102:103], v[96:97] op_sel_hi:[0,1]
	v_pk_fma_f32 v[74:75], v[86:87], v[248:249], v[64:65]
	v_mul_f32_e32 v64, v69, v69
	v_mul_f32_e32 v65, v71, v71
	v_pk_fma_f32 v[72:73], v[88:89], v[250:251], v[66:67]
	v_mul_f32_e32 v66, v75, v75
	v_fmac_f32_e32 v64, v68, v68
	v_fmac_f32_e32 v65, v70, v70
	v_mul_f32_e32 v67, v73, v73
	v_fmac_f32_e32 v66, v74, v74
	v_add_f32_e32 v64, v64, v65
	v_add_f32_e32 v64, v66, v64
	v_fmac_f32_e32 v67, v72, v72
	v_add_f32_e32 v64, v67, v64
	v_add_f32_e32 v64, v91, v64
	ds_bpermute_b32 v65, v122, v64
	v_cvt_pk_bf16_f32 v66, v68, v69
	v_cvt_pk_bf16_f32 v67, v70, v71
	v_cvt_pk_bf16_f32 v68, v74, v75
	v_cvt_pk_bf16_f32 v69, v72, v73
	s_waitcnt lgkmcnt(0)
	v_add_f32_e32 v64, v64, v65
	ds_bpermute_b32 v65, v114, v64
	global_store_dwordx4 v[98:99], v[66:69], off offset:256
	s_and_saveexec_b64 s[26:27], s[4:5]
	s_cbranch_execz .LBB0_947
	v_lshl_add_u64 v[66:67], v[80:81], 2, s[74:75]
	s_waitcnt lgkmcnt(0)
	v_add_f32_e32 v64, v64, v65
	global_atomic_add_f32 v[66:67], v64, off
.LBB0_947:
	s_or_b64 exec, exec, s[26:27]
	v_add_u32_e32 v64, 0x80, v148
	s_waitcnt lgkmcnt(0)
	v_ashrrev_i32_e32 v65, 31, v64
	v_lshlrev_b64 v[66:67], 12, v[64:65]
	v_lshl_add_u64 v[66:67], s[62:63], 0, v[66:67]
	v_lshl_add_u64 v[82:83], v[146:147], 1, v[66:67]
	global_load_dwordx4 v[66:69], v[82:83], off
	global_load_dword v84, v[144:145], off offset:512
	global_load_dwordx4 v[78:81], v[82:83], off offset:256
	s_waitcnt vmcnt(2)
	v_lshlrev_b32_e32 v86, 16, v66
	v_and_b32_e32 v87, 0xffff0000, v66
	v_lshlrev_b32_e32 v66, 16, v67
	v_and_b32_e32 v67, 0xffff0000, v67
	v_lshlrev_b32_e32 v88, 16, v68
	v_and_b32_e32 v89, 0xffff0000, v68
	v_lshlrev_b32_e32 v68, 16, v69
	v_and_b32_e32 v69, 0xffff0000, v69
	s_waitcnt vmcnt(1)
	v_pk_mul_f32 v[86:87], v[84:85], v[86:87] op_sel_hi:[0,1]
	v_pk_mul_f32 v[66:67], v[84:85], v[66:67] op_sel_hi:[0,1]
	v_pk_mul_f32 v[88:89], v[84:85], v[88:89] op_sel_hi:[0,1]
	v_pk_mul_f32 v[68:69], v[84:85], v[68:69] op_sel_hi:[0,1]
	v_pk_fma_f32 v[66:67], v[238:239], v[66:67], v[62:63]
	v_pk_fma_f32 v[70:71], v[236:237], v[86:87], v[60:61]
	v_pk_fma_f32 v[68:69], v[68:69], v[242:243], v[58:59]
	v_pk_fma_f32 v[72:73], v[88:89], v[240:241], v[56:57]
	v_cvt_pk_bf16_f32 v56, v70, v71
	v_cvt_pk_bf16_f32 v57, v66, v67
	v_cvt_pk_bf16_f32 v58, v72, v73
	v_cvt_pk_bf16_f32 v59, v68, v69
	global_store_dwordx4 v[82:83], v[56:59], off
	s_nop 0
	v_mul_f32_e32 v71, v71, v71
	v_mul_f32_e32 v67, v67, v67
	v_mul_f32_e32 v75, v73, v73
	v_fmac_f32_e32 v71, v70, v70
	v_fmac_f32_e32 v67, v66, v66
	v_mul_f32_e32 v76, v69, v69
	v_fmac_f32_e32 v75, v72, v72
	v_add_f32_e32 v77, v71, v67
	v_fmac_f32_e32 v76, v68, v68
	v_add_f32_e32 v75, v75, v77
	s_waitcnt vmcnt(1)
	v_lshlrev_b32_e32 v66, 16, v78
	v_and_b32_e32 v67, 0xffff0000, v78
	v_lshlrev_b32_e32 v68, 16, v79
	v_and_b32_e32 v69, 0xffff0000, v79
	v_add_f32_e32 v75, v76, v75
	v_lshlrev_b32_e32 v70, 16, v80
	v_and_b32_e32 v71, 0xffff0000, v80
	v_lshlrev_b32_e32 v72, 16, v81
	v_and_b32_e32 v73, 0xffff0000, v81
	v_pk_mul_f32 v[66:67], v[84:85], v[66:67] op_sel_hi:[0,1]
	v_pk_mul_f32 v[68:69], v[84:85], v[68:69] op_sel_hi:[0,1]
	v_pk_mul_f32 v[70:71], v[84:85], v[70:71] op_sel_hi:[0,1]
	v_pk_fma_f32 v[54:55], v[246:247], v[68:69], v[54:55]
	v_pk_fma_f32 v[52:53], v[244:245], v[66:67], v[52:53]
	v_pk_mul_f32 v[72:73], v[84:85], v[72:73] op_sel_hi:[0,1]
	v_pk_fma_f32 v[58:59], v[70:71], v[248:249], v[48:49]
	v_mul_f32_e32 v48, v53, v53
	v_mul_f32_e32 v49, v55, v55
	v_pk_fma_f32 v[56:57], v[72:73], v[250:251], v[50:51]
	v_mul_f32_e32 v50, v59, v59
	v_fmac_f32_e32 v48, v52, v52
	v_fmac_f32_e32 v49, v54, v54
	v_mul_f32_e32 v51, v57, v57
	v_fmac_f32_e32 v50, v58, v58
	v_add_f32_e32 v48, v48, v49
	v_add_f32_e32 v48, v50, v48
	v_fmac_f32_e32 v51, v56, v56
	v_add_f32_e32 v48, v51, v48
	v_add_f32_e32 v48, v75, v48
	ds_bpermute_b32 v49, v122, v48
	v_cvt_pk_bf16_f32 v50, v52, v53
	v_cvt_pk_bf16_f32 v51, v54, v55
	v_cvt_pk_bf16_f32 v52, v58, v59
	v_cvt_pk_bf16_f32 v53, v56, v57
	s_waitcnt lgkmcnt(0)
	v_add_f32_e32 v48, v48, v49
	ds_bpermute_b32 v49, v114, v48
	global_store_dwordx4 v[82:83], v[50:53], off offset:256
	s_and_saveexec_b64 s[26:27], s[4:5]
	s_cbranch_execz .LBB0_949
	v_lshl_add_u64 v[50:51], v[64:65], 2, s[74:75]
	s_waitcnt lgkmcnt(0)
	v_add_f32_e32 v48, v48, v49
	global_atomic_add_f32 v[50:51], v48, off
; DI unsigned pk2(float lo, float hi) { const f32x2 v = {lo, hi}; const hwbf16x2 b = __builtin_convertvector(v, hwbf16x2); return __builtin_bit_cast(unsigned, b); }
; DI float fsilu(float v) { return v * frcp(1.f + __expf(-v)); }
;     DI void operator()(const f32x4 (&acc)[2][2][4][2], const Unit& u, int wr, int wc, int fr, int fq) const {
;     ...
;                     } else if (mode == EPI_RESID_NORM) {
;                         const size_t ix = (size_t)row * DM + col;
;                         f32x4 r0, r1;
;                         if (resid) { r0 = *(const f32x4*)(resid + ix); r1 = *(const f32x4*)(resid + ix + 4); }
;                         else {
;                             const u32x4 hb = *(const u32x4*)(O + ix); const float xr = rscale[row];
;                             const f32x4 i0 = *(const f32x4*)(bias + col), i1 = *(const f32x4*)(bias + col + 4);
;                             r0[0] = bflo(hb.x) * xr * i0[0]; r0[1] = bfhi(hb.x) * xr * i0[1]; r0[2] = bflo(hb.y) * xr * i0[2]; r0[3] = bfhi(hb.y) * xr * i0[3];
;                             r1[0] = bflo(hb.z) * xr * i1[0]; r1[1] = bfhi(hb.z) * xr * i1[1]; r1[2] = bflo(hb.w) * xr * i1[2]; r1[3] = bfhi(hb.w) * xr * i1[3];
;                         }
;                         v0 = v0 + r0; v1 = v1 + r1;
;                         if (outf) { *(f32x4*)(outf + ix) = v0; *(f32x4*)(outf + ix + 4) = v1; }
;                         u32x4 w; w.x = pk2(v0[0], v0[1]); w.y = pk2(v0[2], v0[3]); w.z = pk2(v1[0], v1[1]); w.w = pk2(v1[2], v1[3]);
;                         *(u32x4*)(O + ix) = w;
;                         rowacc += (v0[0] * v0[0] + v0[1] * v0[1]) + (v0[2] * v0[2] + v0[3] * v0[3]) + (v1[0] * v1[0] + v1[1] * v1[1]) + (v1[2] * v1[2] + v1[3] * v1[3]);
;                     } else {
;                         v0 = v0 * rs; v1 = v1 * rs;
;                         u32x2 w; w.x = pk2(fsilu(v0[0]) * v1[0], fsilu(v0[1]) * v1[1]); w.y = pk2(fsilu(v0[2]) * v1[2], fsilu(v0[3]) * v1[3]);
;                         *(u32x2*)(O + (size_t)row * ldc + (col >> 1)) = w;
;                     }
;                 }
;                 if (mode == EPI_RESID_NORM) {
;                     rowacc += __shfl_xor(rowacc, 16); rowacc += __shfl_xor(rowacc, 32);
;                     if (fq == 0) atomicAdd(rowsq + row, rowacc);
;                 }
.LBB0_949:
	s_or_b64 exec, exec, s[26:27]
	v_add_u32_e32 v48, 0x90, v148
	s_waitcnt lgkmcnt(0)
	v_ashrrev_i32_e32 v49, 31, v48
	v_lshlrev_b64 v[50:51], 12, v[48:49]
	v_lshl_add_u64 v[50:51], s[62:63], 0, v[50:51]
	v_lshl_add_u64 v[66:67], v[146:147], 1, v[50:51]
	global_load_dwordx4 v[50:53], v[66:67], off
	global_load_dword v68, v[144:145], off offset:576
	global_load_dwordx4 v[62:65], v[66:67], off offset:256
	s_waitcnt vmcnt(2)
	v_lshlrev_b32_e32 v70, 16, v50
	v_and_b32_e32 v71, 0xffff0000, v50
	v_lshlrev_b32_e32 v50, 16, v51
	v_and_b32_e32 v51, 0xffff0000, v51
	v_lshlrev_b32_e32 v72, 16, v52
	v_and_b32_e32 v73, 0xffff0000, v52
	v_lshlrev_b32_e32 v52, 16, v53
	v_and_b32_e32 v53, 0xffff0000, v53
	s_waitcnt vmcnt(1)
	v_pk_mul_f32 v[70:71], v[68:69], v[70:71] op_sel_hi:[0,1]
	v_pk_mul_f32 v[50:51], v[68:69], v[50:51] op_sel_hi:[0,1]
	v_pk_mul_f32 v[72:73], v[68:69], v[72:73] op_sel_hi:[0,1]
	v_pk_mul_f32 v[52:53], v[68:69], v[52:53] op_sel_hi:[0,1]
	v_pk_fma_f32 v[50:51], v[238:239], v[50:51], v[46:47]
	v_pk_fma_f32 v[54:55], v[236:237], v[70:71], v[44:45]
	v_pk_fma_f32 v[52:53], v[52:53], v[242:243], v[42:43]
	v_pk_fma_f32 v[56:57], v[72:73], v[240:241], v[40:41]
	v_cvt_pk_bf16_f32 v40, v54, v55
	v_cvt_pk_bf16_f32 v41, v50, v51
	v_cvt_pk_bf16_f32 v42, v56, v57
	v_cvt_pk_bf16_f32 v43, v52, v53
	global_store_dwordx4 v[66:67], v[40:43], off
	s_nop 0
	v_mul_f32_e32 v55, v55, v55
	v_mul_f32_e32 v51, v51, v51
	v_mul_f32_e32 v59, v57, v57
	v_fmac_f32_e32 v55, v54, v54
	v_fmac_f32_e32 v51, v50, v50
	v_mul_f32_e32 v60, v53, v53
	v_fmac_f32_e32 v59, v56, v56
	v_add_f32_e32 v61, v55, v51
	v_fmac_f32_e32 v60, v52, v52
	v_add_f32_e32 v59, v59, v61
	s_waitcnt vmcnt(1)
	v_lshlrev_b32_e32 v50, 16, v62
	v_and_b32_e32 v51, 0xffff0000, v62
	v_lshlrev_b32_e32 v52, 16, v63
	v_and_b32_e32 v53, 0xffff0000, v63
	v_add_f32_e32 v59, v60, v59
	v_lshlrev_b32_e32 v54, 16, v64
	v_and_b32_e32 v55, 0xffff0000, v64
	v_lshlrev_b32_e32 v56, 16, v65
	v_and_b32_e32 v57, 0xffff0000, v65
	v_pk_mul_f32 v[50:51], v[68:69], v[50:51] op_sel_hi:[0,1]
	v_pk_mul_f32 v[52:53], v[68:69], v[52:53] op_sel_hi:[0,1]
	v_pk_mul_f32 v[54:55], v[68:69], v[54:55] op_sel_hi:[0,1]
	v_pk_fma_f32 v[38:39], v[246:247], v[52:53], v[38:39]
	v_pk_fma_f32 v[36:37], v[244:245], v[50:51], v[36:37]
	v_pk_mul_f32 v[56:57], v[68:69], v[56:57] op_sel_hi:[0,1]
	v_pk_fma_f32 v[42:43], v[54:55], v[248:249], v[32:33]
	v_mul_f32_e32 v32, v37, v37
	v_mul_f32_e32 v33, v39, v39
	v_pk_fma_f32 v[40:41], v[56:57], v[250:251], v[34:35]
	v_mul_f32_e32 v34, v43, v43
	v_fmac_f32_e32 v32, v36, v36
	v_fmac_f32_e32 v33, v38, v38
	v_mul_f32_e32 v35, v41, v41
	v_fmac_f32_e32 v34, v42, v42
	v_add_f32_e32 v32, v32, v33
	v_add_f32_e32 v32, v34, v32
	v_fmac_f32_e32 v35, v40, v40
	v_add_f32_e32 v32, v35, v32
	v_add_f32_e32 v32, v59, v32
	ds_bpermute_b32 v33, v122, v32
	v_cvt_pk_bf16_f32 v34, v36, v37
	v_cvt_pk_bf16_f32 v35, v38, v39
	v_cvt_pk_bf16_f32 v36, v42, v43
	v_cvt_pk_bf16_f32 v37, v40, v41
	s_waitcnt lgkmcnt(0)
	v_add_f32_e32 v32, v32, v33
	ds_bpermute_b32 v33, v114, v32
	global_store_dwordx4 v[66:67], v[34:37], off offset:256
	s_and_saveexec_b64 s[26:27], s[4:5]
	s_cbranch_execz .LBB0_951
	v_lshl_add_u64 v[34:35], v[48:49], 2, s[74:75]
	s_waitcnt lgkmcnt(0)
	v_add_f32_e32 v32, v32, v33
	global_atomic_add_f32 v[34:35], v32, off
; DI unsigned pk2(float lo, float hi) { const f32x2 v = {lo, hi}; const hwbf16x2 b = __builtin_convertvector(v, hwbf16x2); return __builtin_bit_cast(unsigned, b); }
; DI float fsilu(float v) { return v * frcp(1.f + __expf(-v)); }
;     DI void operator()(const f32x4 (&acc)[2][2][4][2], const Unit& u, int wr, int wc, int fr, int fq) const {
;     ...
;                     } else if (mode == EPI_RESID_NORM) {
;                         const size_t ix = (size_t)row * DM + col;
;                         f32x4 r0, r1;
;                         if (resid) { r0 = *(const f32x4*)(resid + ix); r1 = *(const f32x4*)(resid + ix + 4); }
;                         else {
;                             const u32x4 hb = *(const u32x4*)(O + ix); const float xr = rscale[row];
;                             const f32x4 i0 = *(const f32x4*)(bias + col), i1 = *(const f32x4*)(bias + col + 4);
;                             r0[0] = bflo(hb.x) * xr * i0[0]; r0[1] = bfhi(hb.x) * xr * i0[1]; r0[2] = bflo(hb.y) * xr * i0[2]; r0[3] = bfhi(hb.y) * xr * i0[3];
;                             r1[0] = bflo(hb.z) * xr * i1[0]; r1[1] = bfhi(hb.z) * xr * i1[1]; r1[2] = bflo(hb.w) * xr * i1[2]; r1[3] = bfhi(hb.w) * xr * i1[3];
;                         }
;                         v0 = v0 + r0; v1 = v1 + r1;
;                         if (outf) { *(f32x4*)(outf + ix) = v0; *(f32x4*)(outf + ix + 4) = v1; }
;                         u32x4 w; w.x = pk2(v0[0], v0[1]); w.y = pk2(v0[2], v0[3]); w.z = pk2(v1[0], v1[1]); w.w = pk2(v1[2], v1[3]);
;                         *(u32x4*)(O + ix) = w;
;                         rowacc += (v0[0] * v0[0] + v0[1] * v0[1]) + (v0[2] * v0[2] + v0[3] * v0[3]) + (v1[0] * v1[0] + v1[1] * v1[1]) + (v1[2] * v1[2] + v1[3] * v1[3]);
;                     } else {
;                         v0 = v0 * rs; v1 = v1 * rs;
;                         u32x2 w; w.x = pk2(fsilu(v0[0]) * v1[0], fsilu(v0[1]) * v1[1]); w.y = pk2(fsilu(v0[2]) * v1[2], fsilu(v0[3]) * v1[3]);
;                         *(u32x2*)(O + (size_t)row * ldc + (col >> 1)) = w;
;                     }
;                 }
;                 if (mode == EPI_RESID_NORM) {
;                     rowacc += __shfl_xor(rowacc, 16); rowacc += __shfl_xor(rowacc, 32);
;                     if (fq == 0) atomicAdd(rowsq + row, rowacc);
;                 }
.LBB0_951:
	s_or_b64 exec, exec, s[26:27]
	v_add_u32_e32 v32, 0xa0, v148
	s_waitcnt lgkmcnt(0)
	v_ashrrev_i32_e32 v33, 31, v32
	v_lshlrev_b64 v[34:35], 12, v[32:33]
	v_lshl_add_u64 v[34:35], s[62:63], 0, v[34:35]
	v_lshl_add_u64 v[50:51], v[146:147], 1, v[34:35]
	global_load_dwordx4 v[34:37], v[50:51], off
	global_load_dword v52, v[144:145], off offset:640
	global_load_dwordx4 v[46:49], v[50:51], off offset:256
	s_waitcnt vmcnt(2)
	v_lshlrev_b32_e32 v54, 16, v34
	v_and_b32_e32 v55, 0xffff0000, v34
	v_lshlrev_b32_e32 v34, 16, v35
	v_and_b32_e32 v35, 0xffff0000, v35
	v_lshlrev_b32_e32 v56, 16, v36
	v_and_b32_e32 v57, 0xffff0000, v36
	v_lshlrev_b32_e32 v36, 16, v37
	v_and_b32_e32 v37, 0xffff0000, v37
	s_waitcnt vmcnt(1)
	v_pk_mul_f32 v[54:55], v[52:53], v[54:55] op_sel_hi:[0,1]
	v_pk_mul_f32 v[34:35], v[52:53], v[34:35] op_sel_hi:[0,1]
	v_pk_mul_f32 v[56:57], v[52:53], v[56:57] op_sel_hi:[0,1]
	v_pk_mul_f32 v[36:37], v[52:53], v[36:37] op_sel_hi:[0,1]
	v_pk_fma_f32 v[34:35], v[238:239], v[34:35], v[30:31]
	v_pk_fma_f32 v[38:39], v[236:237], v[54:55], v[28:29]
	v_pk_fma_f32 v[36:37], v[36:37], v[242:243], v[26:27]
	v_pk_fma_f32 v[40:41], v[56:57], v[240:241], v[24:25]
	v_cvt_pk_bf16_f32 v24, v38, v39
	v_cvt_pk_bf16_f32 v25, v34, v35
	v_cvt_pk_bf16_f32 v26, v40, v41
	v_cvt_pk_bf16_f32 v27, v36, v37
	global_store_dwordx4 v[50:51], v[24:27], off
	s_nop 0
	v_mul_f32_e32 v39, v39, v39
	v_mul_f32_e32 v35, v35, v35
	v_mul_f32_e32 v43, v41, v41
	v_fmac_f32_e32 v39, v38, v38
	v_fmac_f32_e32 v35, v34, v34
	v_mul_f32_e32 v44, v37, v37
	v_fmac_f32_e32 v43, v40, v40
	v_add_f32_e32 v45, v39, v35
	v_fmac_f32_e32 v44, v36, v36
	v_add_f32_e32 v43, v43, v45
	s_waitcnt vmcnt(1)
	v_lshlrev_b32_e32 v34, 16, v46
	v_and_b32_e32 v35, 0xffff0000, v46
	v_lshlrev_b32_e32 v36, 16, v47
	v_and_b32_e32 v37, 0xffff0000, v47
	v_add_f32_e32 v43, v44, v43
	v_lshlrev_b32_e32 v38, 16, v48
	v_and_b32_e32 v39, 0xffff0000, v48
	v_lshlrev_b32_e32 v40, 16, v49
	v_and_b32_e32 v41, 0xffff0000, v49
	v_pk_mul_f32 v[34:35], v[52:53], v[34:35] op_sel_hi:[0,1]
	v_pk_mul_f32 v[36:37], v[52:53], v[36:37] op_sel_hi:[0,1]
	v_pk_mul_f32 v[38:39], v[52:53], v[38:39] op_sel_hi:[0,1]
	v_pk_fma_f32 v[22:23], v[246:247], v[36:37], v[22:23]
	v_pk_fma_f32 v[20:21], v[244:245], v[34:35], v[20:21]
	v_pk_mul_f32 v[40:41], v[52:53], v[40:41] op_sel_hi:[0,1]
	v_pk_fma_f32 v[26:27], v[38:39], v[248:249], v[16:17]
	v_mul_f32_e32 v16, v21, v21
	v_mul_f32_e32 v17, v23, v23
	v_pk_fma_f32 v[24:25], v[40:41], v[250:251], v[18:19]
	v_mul_f32_e32 v18, v27, v27
	v_fmac_f32_e32 v16, v20, v20
	v_fmac_f32_e32 v17, v22, v22
	v_mul_f32_e32 v19, v25, v25
	v_fmac_f32_e32 v18, v26, v26
	v_add_f32_e32 v16, v16, v17
	v_add_f32_e32 v16, v18, v16
	v_fmac_f32_e32 v19, v24, v24
	v_add_f32_e32 v16, v19, v16
	v_add_f32_e32 v16, v43, v16
	ds_bpermute_b32 v17, v122, v16
	v_cvt_pk_bf16_f32 v18, v20, v21
	v_cvt_pk_bf16_f32 v19, v22, v23
	v_cvt_pk_bf16_f32 v20, v26, v27
	v_cvt_pk_bf16_f32 v21, v24, v25
	s_waitcnt lgkmcnt(0)
	v_add_f32_e32 v16, v16, v17
	ds_bpermute_b32 v17, v114, v16
	global_store_dwordx4 v[50:51], v[18:21], off offset:256
	s_and_saveexec_b64 s[26:27], s[4:5]
	s_cbranch_execz .LBB0_953
	v_lshl_add_u64 v[18:19], v[32:33], 2, s[74:75]
	s_waitcnt lgkmcnt(0)
	v_add_f32_e32 v16, v16, v17
	global_atomic_add_f32 v[18:19], v16, off
.LBB0_953:
	s_or_b64 exec, exec, s[26:27]
	v_add_u32_e32 v16, 0xb0, v148
	s_waitcnt lgkmcnt(0)
	v_ashrrev_i32_e32 v17, 31, v16
	v_lshlrev_b64 v[18:19], 12, v[16:17]
	v_lshl_add_u64 v[18:19], s[62:63], 0, v[18:19]
	v_lshl_add_u64 v[34:35], v[146:147], 1, v[18:19]
	global_load_dwordx4 v[18:21], v[34:35], off
	global_load_dword v36, v[144:145], off offset:704
	global_load_dwordx4 v[30:33], v[34:35], off offset:256
	s_waitcnt vmcnt(2)
	v_lshlrev_b32_e32 v38, 16, v18
	v_and_b32_e32 v39, 0xffff0000, v18
	v_lshlrev_b32_e32 v18, 16, v19
	v_and_b32_e32 v19, 0xffff0000, v19
	v_lshlrev_b32_e32 v40, 16, v20
	v_and_b32_e32 v41, 0xffff0000, v20
	v_lshlrev_b32_e32 v20, 16, v21
	v_and_b32_e32 v21, 0xffff0000, v21
	s_waitcnt vmcnt(1)
	v_pk_mul_f32 v[38:39], v[36:37], v[38:39] op_sel_hi:[0,1]
	v_pk_mul_f32 v[18:19], v[36:37], v[18:19] op_sel_hi:[0,1]
	v_pk_mul_f32 v[40:41], v[36:37], v[40:41] op_sel_hi:[0,1]
	v_pk_mul_f32 v[20:21], v[36:37], v[20:21] op_sel_hi:[0,1]
	v_pk_fma_f32 v[18:19], v[238:239], v[18:19], v[14:15]
	v_pk_fma_f32 v[22:23], v[236:237], v[38:39], v[12:13]
	v_pk_fma_f32 v[20:21], v[20:21], v[242:243], v[10:11]
	v_pk_fma_f32 v[24:25], v[40:41], v[240:241], v[8:9]
	v_cvt_pk_bf16_f32 v8, v22, v23
	v_cvt_pk_bf16_f32 v9, v18, v19
	v_cvt_pk_bf16_f32 v10, v24, v25
	v_cvt_pk_bf16_f32 v11, v20, v21
	global_store_dwordx4 v[34:35], v[8:11], off
	s_nop 0
	v_mul_f32_e32 v23, v23, v23
	v_mul_f32_e32 v19, v19, v19
	v_mul_f32_e32 v27, v25, v25
	v_fmac_f32_e32 v23, v22, v22
	v_fmac_f32_e32 v19, v18, v18
	v_mul_f32_e32 v28, v21, v21
	v_fmac_f32_e32 v27, v24, v24
	v_add_f32_e32 v29, v23, v19
	v_fmac_f32_e32 v28, v20, v20
	v_add_f32_e32 v27, v27, v29
	s_waitcnt vmcnt(1)
	v_lshlrev_b32_e32 v18, 16, v30
	v_and_b32_e32 v19, 0xffff0000, v30
	v_lshlrev_b32_e32 v20, 16, v31
	v_and_b32_e32 v21, 0xffff0000, v31
	v_add_f32_e32 v27, v28, v27
	v_lshlrev_b32_e32 v22, 16, v32
	v_and_b32_e32 v23, 0xffff0000, v32
	v_lshlrev_b32_e32 v24, 16, v33
	v_and_b32_e32 v25, 0xffff0000, v33
	v_pk_mul_f32 v[18:19], v[36:37], v[18:19] op_sel_hi:[0,1]
	v_pk_mul_f32 v[20:21], v[36:37], v[20:21] op_sel_hi:[0,1]
	v_pk_mul_f32 v[22:23], v[36:37], v[22:23] op_sel_hi:[0,1]
	v_pk_fma_f32 v[6:7], v[246:247], v[20:21], v[6:7]
	v_pk_fma_f32 v[4:5], v[244:245], v[18:19], v[4:5]
	v_pk_mul_f32 v[24:25], v[36:37], v[24:25] op_sel_hi:[0,1]
	v_pk_fma_f32 v[10:11], v[22:23], v[248:249], v[0:1]
	v_mul_f32_e32 v0, v5, v5
	v_mul_f32_e32 v1, v7, v7
	v_pk_fma_f32 v[8:9], v[24:25], v[250:251], v[2:3]
	v_mul_f32_e32 v2, v11, v11
	v_fmac_f32_e32 v0, v4, v4
	v_fmac_f32_e32 v1, v6, v6
	v_mul_f32_e32 v3, v9, v9
	v_fmac_f32_e32 v2, v10, v10
	v_add_f32_e32 v0, v0, v1
	v_add_f32_e32 v0, v2, v0
	v_fmac_f32_e32 v3, v8, v8
	v_add_f32_e32 v0, v3, v0
	v_add_f32_e32 v0, v27, v0
	ds_bpermute_b32 v1, v122, v0
	v_cvt_pk_bf16_f32 v2, v4, v5
	v_cvt_pk_bf16_f32 v3, v6, v7
	v_cvt_pk_bf16_f32 v4, v10, v11
	v_cvt_pk_bf16_f32 v5, v8, v9
	s_waitcnt lgkmcnt(0)
	v_add_f32_e32 v0, v0, v1
	ds_bpermute_b32 v1, v114, v0
	global_store_dwordx4 v[34:35], v[2:5], off offset:256
	s_and_saveexec_b64 s[26:27], s[4:5]
	s_cbranch_execz .LBB0_955
	v_lshl_add_u64 v[2:3], v[16:17], 2, s[74:75]
	s_waitcnt lgkmcnt(0)
	v_add_f32_e32 v0, v0, v1
	global_atomic_add_f32 v[2:3], v0, off
